# GEMM phases: static s_setprio 1 for waves 0-3 (wr==0) instead of waves 4-7, per-phase flips removed
# baseline (speedup 1.0000x reference)
;     __device__ __forceinline__ void prefetch(const Unit& u, PG8_LAS unsigned char* slot, int tid, int wid) const { if (f.on) xslot_fetch(f.st + 8 * (u.pm * BM), f.c1 + u.pn * BM, f.c2 + u.pn * BM, slot, tid, wid); }
;     __device__ __forceinline__ void prefetch(const Unit& u, PG8_LAS unsigned char* slot, int tid, int wid) const { xslot_fetch(f.st + 8 * (u.pm * BM), f.c1 + u.pn * BM, f.c2 + u.pn * BM, slot, tid, wid); }
;     __device__ __forceinline__ void prefetch(const Unit& u, PG8_LAS unsigned char* slot, int tid, int wid) const { if (st_prev) xslot_fetch(st_prev + 8 * (u.pm * BM), gp + u.pn * BM, bp + u.pn * BM, slot, tid, wid); }
; #define PG8_BAR __builtin_amdgcn_s_barrier()
; template <class Epi, class Sched, bool ALIGN_EPI = false, bool SP2 = false>
; __device__ __forceinline__ void gemm_phase(PG8_LAS unsigned char* lds, const Gemm g, const Sched& S, const Epi& E) {
;     ...
;     for (int i = 0; i < 2; ++i) { int R, C; stage_rc(tid * 16 + i * 8192, R, C); const int Rb = Epi::PERM ? ((R & ~31) + perm32(R & 31)) : R;
;         voffA[i] = (unsigned)(R * K + C) * 2u; voffB[i] = (unsigned)(Rb * K + C) * 2u; }
;     const size_t kstep = (size_t)(BK * 2);
;     const size_t hstep = (size_t)HALF * K * 2;
;     const size_t tstep = 2 * hstep;
;     const unsigned ldsw = (unsigned)wid * 1024u;
;     const int aoff = lds_byte(wr * 64 + fr, fq * 8), boff = lds_byte(wc * 32 + fr, fq * 8);
;     ...
;     Unit cur, nxt; int ui = 0;
;     if (!S.next(0, cur)) return;
;     f32x4 acc[2][2][4][2];
; #pragma unroll
;     for (int a = 0; a < 2; ++a)
; #pragma unroll
;         for (int b = 0; b < 2; ++b)
; #pragma unroll
;             for (int m = 0; m < 4; ++m)
; #pragma unroll
;                 for (int n = 0; n < 2; ++n) acc[a][b][m][n] = (f32x4){0.f, 0.f, 0.f, 0.f};
;     bf16x8 At[4][2], B0[2][2], B1[2][2];
;     typename Epi::Pre pre;
;     const char* cA = (const char*)g.A + (size_t)cur.pm * tstep; const char* cB = (const char*)g.Bt + (size_t)cur.pn * tstep;
;     S.a_ready(cur);
;     E.prefetch(cur, lds + XSLOT_OFF, tid, wid);
;     if constexpr (SP2) {
;         PG8_STAGE(PG8_SB(0, 0), cB, voffB); PG8_STAGE(PG8_SB(0, 1), cB + hstep, voffB); PG8_STAGE(PG8_SA(0, 0), cA, voffA); PG8_STAGE(PG8_SA(0, 1), cA + hstep, voffA);
;         if (wr == 1) PG8_BAR;
.LBB0_51:
	v_bfe_i32 v3, v4, 27, 1
	v_lshlrev_b32_e32 v1, 4, v4
	v_lshrrev_b32_e32 v3, 22, v3
	v_add_u32_e32 v3, v1, v3
	v_and_b32_e32 v3, 0xfffffc00, v3
	v_sub_u32_e32 v3, v1, v3
	v_lshrrev_b32_e32 v8, 4, v3
	v_lshrrev_b32_e32 v0, 26, v5
	v_bitop3_b32 v8, v8, v3, 32 bitop3:0x6c
	v_ashrrev_i32_e32 v3, 31, v3
	v_add_u32_e32 v0, v4, v0
	v_lshrrev_b32_e32 v3, 26, v3
	v_ashrrev_i32_e32 v0, 6, v0
	v_add_u32_e32 v3, v8, v3
	v_lshlrev_b32_e32 v9, 3, v0
	v_ashrrev_i32_e32 v10, 6, v3
	v_lshlrev_b32_e32 v0, 5, v0
	v_and_b32_e32 v3, 32, v0
	v_mul_i32_i24_e32 v0, 64, v10
	v_and_b32_e32 v9, -16, v9
	v_sub_u32_e32 v0, v8, v0
	v_mov_b32_e32 v12, 1
	v_add_u32_e32 v9, v10, v9
	v_ashrrev_i16_sdwa v0, v12, sext(v0) dst_sel:DWORD dst_unused:UNUSED_PAD src0_sel:DWORD src1_sel:BYTE_0
	v_bfe_i32 v20, v0, 0, 16
	v_lshlrev_b32_e32 v0, 1, v9
	v_lshrrev_b32_e32 v11, 2, v9
	v_and_b32_e32 v10, 3, v10
	s_mov_b32 s4, 0x7fffffe0
	v_and_b32_e32 v0, 24, v0
	v_and_b32_e32 v11, 4, v11
	v_and_or_b32 v10, v9, s4, v10
	v_or3_b32 v10, v10, v11, v0
	v_add_u32_e32 v8, v3, v20
	v_mul_lo_u32 v21, v9, s26
	v_mul_lo_u32 v9, v10, s26
	v_add_u32_e32 v1, 0x2000, v1
	v_add_lshl_u32 v0, v8, v21, 1
	v_add_lshl_u32 v172, v9, v8, 1
	v_ashrrev_i32_e32 v8, 31, v1
	v_lshrrev_b32_e32 v8, 22, v8
	v_add_u32_e32 v8, v1, v8
	v_ashrrev_i32_e32 v8, 10, v8
	v_mul_i32_i24_e32 v9, 0x400, v8
	v_sub_u32_e32 v1, v1, v9
	v_lshrrev_b32_e32 v9, 4, v1
	v_bitop3_b32 v1, v9, v1, 32 bitop3:0x6c
	v_ashrrev_i32_e32 v10, 31, v1
	s_lshl_b32 s61, s26, 9
	v_lshrrev_b32_e32 v10, 26, v10
	s_lshl_b32 s8, s26, 8
	s_mul_i32 s15, s61, s23
	v_readlane_b32 s24, v250, 6
	v_lshlrev_b32_e32 v9, 3, v8
	v_add_u32_e32 v10, v1, v10
	s_mul_hi_i32 s14, s61, s23
	v_readlane_b32 s25, v250, 7
	s_add_u32 s46, s24, s15
	v_and_b32_e32 v9, -16, v9
	v_ashrrev_i32_e32 v11, 6, v10
	v_lshlrev_b32_e32 v8, 5, v8
	s_addc_u32 s47, s25, s14
	s_mul_i32 s15, s61, s22
	v_add_u32_e32 v9, v11, v9
	v_and_b32_e32 v22, 32, v8
	v_and_b32_e32 v8, 0xc0, v10
	s_mul_hi_i32 s14, s61, s22
	s_add_u32 s48, s16, s15
	v_sub_u32_e32 v1, v1, v8
	v_lshlrev_b32_e32 v8, 1, v9
	v_lshrrev_b32_e32 v10, 2, v9
	v_and_b32_e32 v11, 3, v11
	s_addc_u32 s49, s17, s14
	v_ashrrev_i16_sdwa v1, v12, sext(v1) dst_sel:DWORD dst_unused:UNUSED_PAD src0_sel:DWORD src1_sel:BYTE_0
	v_and_b32_e32 v8, 24, v8
	v_and_b32_e32 v10, 4, v10
	v_and_or_b32 v11, v9, s4, v11
	s_add_i32 s62, s60, 0
	v_bfe_i32 v23, v1, 0, 16
	v_or3_b32 v8, v11, v10, v8
	s_add_i32 m0, s62, 0x10000
	v_add_u32_e32 v1, v22, v23
	v_mul_lo_u32 v8, v8, s26
	s_ashr_i32 s27, s30, 8
	global_load_lds_dwordx4 v172, s[48:49]
	s_add_i32 m0, s62, 0x12000
	v_add_lshl_u32 v176, v8, v1, 1
	s_add_u32 s24, s48, s8
	global_load_lds_dwordx4 v176, s[48:49]
	s_addc_u32 s25, s49, 0
	s_add_i32 m0, s62, 0x14000
	v_mov_b32_e32 v173, v2
	v_mov_b32_e32 v177, v2
	global_load_lds_dwordx4 v172, s[24:25]
	s_add_i32 m0, s62, 0x16000
	s_add_i32 s63, s62, 0x2000
	v_mul_lo_u32 v24, v9, s26
	v_lshl_add_u64 v[12:13], s[24:25], 0, v[172:173]
	v_lshl_add_u64 v[14:15], s[24:25], 0, v[176:177]
	global_load_lds_dwordx4 v176, s[24:25]
	s_mov_b32 m0, s62
	s_add_u32 s24, s46, s8
	v_add_lshl_u32 v174, v1, v24, 1
	global_load_lds_dwordx4 v0, s[46:47]
	s_mov_b32 m0, s63
	s_addc_u32 s25, s47, 0
	s_add_i32 s64, s62, 0x4000
	global_load_lds_dwordx4 v174, s[46:47]
	s_mov_b32 m0, s64
	s_add_i32 s65, s62, 0x6000
	global_load_lds_dwordx4 v0, s[24:25]
	s_mov_b32 m0, s65
	v_writelane_b32 v253, s68, 12
	global_load_lds_dwordx4 v174, s[24:25]
	s_nop 0
	v_writelane_b32 v253, s69, 13
	v_writelane_b32 v253, s70, 14
	v_writelane_b32 v253, s71, 15
	v_writelane_b32 v253, s72, 16
	v_writelane_b32 v253, s73, 17
	v_writelane_b32 v254, s76, 41
	v_writelane_b32 v253, s74, 18
	v_mov_b32_e32 v1, v2
	v_mov_b32_e32 v175, v2
	s_cmp_eq_u32 s27, 1
	v_writelane_b32 v254, s77, 42
	v_writelane_b32 v253, s75, 19
	v_lshl_add_u64 v[8:9], s[48:49], 0, v[172:173]
	v_lshl_add_u64 v[10:11], s[48:49], 0, v[176:177]
	v_lshl_add_u64 v[16:17], s[46:47], 0, v[0:1]
	v_lshl_add_u64 v[18:19], s[46:47], 0, v[174:175]
	s_cselect_b64 s[24:25], -1, 0
	s_cmp_lg_u32 s27, 1
	s_setprio 1
	s_cbranch_scc1 .LBB0_53
	s_setprio 0
	s_barrier

; #define PG8_LAS __attribute__((address_space(3)))
;     __host__ __device__ bool next(int i, Unit& u) const {
;         const long L = (long)i * G + c; if (L >= nwg) return false;
;         int wgid = (int)L; { const int q = nwg / NXCD, r = nwg % NXCD, xcd = wgid % NXCD, off = wgid / NXCD; wgid = (xcd < r ? xcd * (q + 1) : r * (q + 1) + (xcd - r) * q) + off; }
;         const int nig = WGM * nN, gid = wgid / nig, fm = gid * WGM, gsz = (nM - fm) < WGM ? (nM - fm) : WGM;
;         u.pm = fm + ((wgid % nig) % gsz); u.pn = (wgid % nig) / gsz; return true;
;     }
; __device__ __forceinline__ unsigned cvt_pk_bf16(float lo, float hi) { unsigned r; asm volatile("v_cvt_pk_bf16_f32 %0, %1, %2" : "=v"(r) : "v"(lo), "v"(hi)); return r; }
; __device__ __forceinline__ void xslot_fetch(const float* st_rows, const float* v1, const float* v2, PG8_LAS unsigned char* slot, int tid, int wid) {
;     __builtin_amdgcn_global_load_lds((const unsigned*)(st_rows + tid * 4), (PG8_LAS unsigned*)(slot + wid * 1024), 16, 0, 0);
;     const float* vp = wid < 4 ? v1 + tid : v2 + (tid - 256);
;     __builtin_amdgcn_global_load_lds((const unsigned*)vp, (PG8_LAS unsigned*)(slot + 8192 + wid * 256), 4, 0, 0);
; template <class Epi, class Sched, bool ALIGN_EPI = false, bool SP2 = false>
; __device__ __forceinline__ void gemm_phase(PG8_LAS unsigned char* lds, const Gemm g, const Sched& S, const Epi& E) {
;     ...
;     for (int i = 0; i < 2; ++i) { int R, C; stage_rc(tid * 16 + i * 8192, R, C); const int Rb = Epi::PERM ? ((R & ~31) + perm32(R & 31)) : R;
;         voffA[i] = (unsigned)(R * K + C) * 2u; voffB[i] = (unsigned)(Rb * K + C) * 2u; }
;     const size_t kstep = (size_t)(BK * 2);
;     const size_t hstep = (size_t)HALF * K * 2;
;     const size_t tstep = 2 * hstep;
;     const unsigned ldsw = (unsigned)wid * 1024u;
;     const int aoff = lds_byte(wr * 64 + fr, fq * 8), boff = lds_byte(wc * 32 + fr, fq * 8);
;     ...
;     Unit cur, nxt; int ui = 0;
;     if (!S.next(0, cur)) return;
;     f32x4 acc[2][2][4][2];
; #pragma unroll
;     for (int a = 0; a < 2; ++a)
; #pragma unroll
;         for (int b = 0; b < 2; ++b)
; #pragma unroll
;             for (int m = 0; m < 4; ++m)
; #pragma unroll
;                 for (int n = 0; n < 2; ++n) acc[a][b][m][n] = (f32x4){0.f, 0.f, 0.f, 0.f};
;     bf16x8 At[4][2], B0[2][2], B1[2][2];
;     typename Epi::Pre pre;
.LBB0_445:
	v_mov_b32_e32 v4, v220
	s_cmpk_gt_i32 s8, 0xaff
	v_readfirstlane_b32 s4, v4
	s_cbranch_scc1 .LBB0_463
	v_lshlrev_b32_e32 v1, 4, v4
	v_add_u32_e32 v0, 0x2000, v1
	v_ashrrev_i32_e32 v3, 31, v0
	v_lshrrev_b32_e32 v3, 22, v3
	v_add_u32_e32 v3, v0, v3
	v_ashrrev_i32_e32 v18, 10, v3
	s_lshl_b64 s[2:3], s[2:3], 2
	v_readlane_b32 s14, v250, 22
	v_mul_i32_i24_e32 v3, 0x400, v18
	v_readlane_b32 s15, v250, 23
	s_add_u32 s2, s14, s2
	v_sub_u32_e32 v0, v0, v3
	s_addc_u32 s3, s15, s3
	s_ashr_i32 s5, s4, 6
	v_lshrrev_b32_e32 v3, 4, v0
	s_ashr_i32 s16, s4, 8
	s_lshl_b32 s13, s5, 10
	s_lshl_b64 s[0:1], s[0:1], 2
	v_readlane_b32 s14, v250, 20
	v_bitop3_b32 v0, v3, v0, 32 bitop3:0x6c
	v_readlane_b32 s15, v250, 21
	s_add_u32 s14, s14, s0
	v_ashrrev_i32_e32 v3, 31, v0
	s_addc_u32 s15, s15, s1
	v_readlane_b32 s0, v253, 2
	v_lshrrev_b32_e32 v3, 26, v3
	v_readlane_b32 s1, v253, 3
	s_mov_b32 s18, s0
	v_add_u32_e32 v3, v0, v3
	s_waitcnt lgkmcnt(0)
	v_lshlrev_b32_e32 v5, 3, v18
	s_mul_i32 s1, s18, 0xb00000
	v_readlane_b32 s17, v250, 36
	v_ashrrev_i32_e32 v19, 6, v3
	v_and_b32_e32 v5, -16, v5
	s_mul_hi_i32 s0, s0, 0xb00000
	s_add_u32 s28, s17, s1
	v_readlane_b32 s1, v250, 37
	v_add_u32_e32 v5, v19, v5
	s_addc_u32 s29, s1, s0
	v_and_b32_e32 v6, 3, v19
	s_mov_b32 s0, 0x1fffe0
	v_lshrrev_b32_e32 v7, 2, v5
	v_lshlrev_b32_e32 v8, 1, v5
	v_and_b32_e32 v3, 0xc0, v3
	v_and_or_b32 v6, v5, s0, v6
	v_and_b32_e32 v7, 4, v7
	v_and_b32_e32 v8, 24, v8
	v_sub_u32_e32 v0, v0, v3
	v_mov_b32_e32 v9, 1
	v_or3_b32 v6, v6, v7, v8
	v_lshlrev_b32_e32 v7, 5, v18
	v_ashrrev_i16_sdwa v0, v9, sext(v0) dst_sel:DWORD dst_unused:UNUSED_PAD src0_sel:DWORD src1_sel:BYTE_0
	v_and_b32_e32 v7, 32, v7
	v_bfe_i32 v20, v0, 0, 16
	v_add_lshl_u32 v3, v7, v20, 1
	v_lshl_add_u32 v0, v6, 11, v3
	v_lshl_add_u32 v164, v5, 11, v3
	v_bfe_i32 v3, v4, 27, 1
	v_lshrrev_b32_e32 v3, 22, v3
	v_add_u32_e32 v3, v1, v3
	v_and_b32_e32 v3, 0xfffffc00, v3
	v_sub_u32_e32 v1, v1, v3
	v_lshrrev_b32_e32 v3, 4, v1
	v_bitop3_b32 v3, v3, v1, 32 bitop3:0x6c
	v_ashrrev_i32_e32 v1, 31, v1
	v_lshrrev_b32_e32 v1, 26, v1
	v_add_u32_e32 v1, v3, v1
	v_ashrrev_i32_e32 v5, 31, v4
	v_ashrrev_i32_e32 v21, 6, v1
	v_lshrrev_b32_e32 v1, 26, v5
	v_add_u32_e32 v1, v4, v1
	v_ashrrev_i32_e32 v22, 6, v1
	v_lshlrev_b32_e32 v1, 3, v22
	v_and_b32_e32 v1, -16, v1
	v_add_u32_e32 v1, v21, v1
	v_and_b32_e32 v6, 3, v21
	s_ashr_i32 s30, s8, 31
	v_and_or_b32 v6, v1, s0, v6
	s_lshr_b32 s0, s30, 29
	s_add_i32 s0, s8, s0
	s_ashr_i32 s1, s0, 3
	s_and_b32 s0, s0, -8
	s_sub_i32 s0, s8, s0
	s_cmp_lt_i32 s0, 0
	s_movk_i32 s17, 0x161
	s_cselect_b32 s17, s17, 0x160
	s_mul_i32 s0, s0, s17
	s_add_i32 s0, s0, s1
	s_mul_hi_i32 s1, s0, 0x2e8ba2e9
	s_lshr_b32 s17, s1, 31
	s_ashr_i32 s1, s1, 5
	s_add_i32 s1, s1, s17
	s_lshl_b32 s17, s1, 3
	s_mulk_i32 s1, 0xb0
	s_sub_i32 s1, s0, s1
	s_bfe_u32 s0, s1, 0x3001c
	s_add_i32 s18, s1, s0
	s_sext_i32_i16 s19, s18
	s_and_b32 s18, s18, 0xfff8
	s_sub_i32 s1, s1, s18
	s_sext_i32_i16 s1, s1
	s_lshr_b32 s0, s19, 3
	s_add_i32 s22, s17, s1
	s_ashr_i32 s23, s22, 31
	s_bfe_i64 s[0:1], s[0:1], 0x100000
	s_ashr_i32 s44, s19, 3
	s_lshl_b64 s[18:19], s[22:23], 19
	s_lshl_b64 s[0:1], s[0:1], 19
	s_mov_b32 s56, s24
	s_add_u32 s24, s28, s0
	s_addc_u32 s25, s29, s1
	s_lshl_b32 s0, s22, 11
	s_ashr_i32 s1, s0, 31
	v_lshrrev_b32_e32 v7, 2, v1
	v_lshlrev_b32_e32 v8, 1, v1
	s_lshl_b64 s[0:1], s[0:1], 2
	v_readlane_b32 s20, v250, 18
	v_and_b32_e32 v7, 4, v7
	v_and_b32_e32 v8, 24, v8
	v_readlane_b32 s21, v250, 19
	s_add_u32 s0, s20, s0
	v_or3_b32 v6, v6, v7, v8
	v_mul_i32_i24_e32 v8, 64, v21
	s_addc_u32 s1, s21, s1
	s_lshl_b32 s20, s44, 8
	v_sub_u32_e32 v3, v3, v8
	s_ashr_i32 s21, s20, 31
	v_lshlrev_b32_e32 v7, 5, v22
	v_ashrrev_i16_sdwa v3, v9, sext(v3) dst_sel:DWORD dst_unused:UNUSED_PAD src0_sel:DWORD src1_sel:BYTE_0
	s_lshl_b64 s[20:21], s[20:21], 2
	v_and_b32_e32 v7, 32, v7
	v_bfe_i32 v23, v3, 0, 16
	s_add_u32 s26, s14, s20
	v_add_lshl_u32 v3, v7, v23, 1
	s_addc_u32 s27, s15, s21
	v_lshl_add_u32 v166, v6, 11, v3
	s_add_u32 s20, s2, s20
	v_lshlrev_b32_e32 v6, 2, v4
	s_addc_u32 s21, s3, s21
	v_ashrrev_i32_e32 v7, 31, v6
	s_add_i32 s23, s13, 0
	v_lshl_add_u64 v[8:9], v[6:7], 2, s[0:1]
	s_add_i32 m0, s23, 0x20000
	s_cmp_lt_i32 s5, 4
	global_load_lds_dwordx4 v[8:9], off
	v_lshlrev_b64 v[8:9], 2, v[4:5]
	s_movk_i32 s0, 0xfc00
	v_lshl_add_u64 v[12:13], s[20:21], 0, v[8:9]
	s_mov_b32 s1, -1
	s_cselect_b64 s[38:39], -1, 0
	s_lshl_b32 s31, s5, 8
	v_lshl_add_u64 v[10:11], s[26:27], 0, v[8:9]
	v_lshl_add_u64 v[12:13], v[12:13], 0, s[0:1]
	s_add_i32 s0, s31, 0
	v_cndmask_b32_e64 v11, v13, v11, s[38:39]
	v_cndmask_b32_e64 v10, v12, v10, s[38:39]
	s_add_i32 m0, s0, 0x22000
	v_lshl_add_u32 v168, v1, 11, v3
	global_load_lds_dword v[10:11], off
	s_add_i32 m0, s23, 0x10000
	v_mov_b32_e32 v167, v2
	global_load_lds_dwordx4 v166, s[24:25]
	s_add_i32 m0, s23, 0x12000
	s_add_u32 s0, s24, 0x40000
	global_load_lds_dwordx4 v0, s[24:25]
	s_addc_u32 s1, s25, 0
	s_add_i32 m0, s23, 0x14000
	v_mov_b32_e32 v1, v2
	global_load_lds_dwordx4 v166, s[0:1]
	s_add_i32 m0, s23, 0x16000
	v_mov_b32_e32 v169, v2
	global_load_lds_dwordx4 v0, s[0:1]
	v_readlane_b32 s0, v250, 4
	v_readlane_b32 s1, v250, 5
	s_add_u32 s26, s0, s18
	s_addc_u32 s27, s1, s19
	s_add_i32 s34, s23, 0x2000
	s_mov_b32 m0, s23
	s_add_u32 s0, s26, 0x40000
	global_load_lds_dwordx4 v168, s[26:27]
	s_mov_b32 m0, s34
	s_addc_u32 s1, s27, 0
	s_add_i32 s35, s23, 0x4000
	global_load_lds_dwordx4 v164, s[26:27]
	s_mov_b32 m0, s35
	s_add_i32 s36, s23, 0x6000
	global_load_lds_dwordx4 v168, s[0:1]
	s_mov_b32 m0, s36
	v_mov_b32_e32 v165, v2
	global_load_lds_dwordx4 v164, s[0:1]
	s_cmp_eq_u32 s16, 1
	v_mov_b32_e32 v242, 0x358637bd
	v_lshl_add_u64 v[16:17], s[24:25], 0, v[166:167]
	s_waitcnt lgkmcnt(0)
	v_lshl_add_u64 v[14:15], s[24:25], 0, v[0:1]
	v_lshl_add_u64 v[10:11], s[26:27], 0, v[168:169]
	s_cselect_b64 s[0:1], -1, 0
	s_cmp_lg_u32 s16, 1
	v_lshl_add_u64 v[12:13], s[26:27], 0, v[164:165]
	s_setprio 1
	s_cbranch_scc1 .LBB0_448
	s_setprio 0
	s_barrier

;     __device__ __forceinline__ void prefetch(const Unit& u, PG8_LAS unsigned char* slot, int tid, int wid) const { if (f.on) xslot_fetch(f.st + 8 * (u.pm * BM), f.c1 + u.pn * BM, f.c2 + u.pn * BM, slot, tid, wid); }
;     __device__ __forceinline__ void prefetch(const Unit& u, PG8_LAS unsigned char* slot, int tid, int wid) const { xslot_fetch(f.st + 8 * (u.pm * BM), f.c1 + u.pn * BM, f.c2 + u.pn * BM, slot, tid, wid); }
;     __device__ __forceinline__ void prefetch(const Unit& u, PG8_LAS unsigned char* slot, int tid, int wid) const { if (st_prev) xslot_fetch(st_prev + 8 * (u.pm * BM), gp + u.pn * BM, bp + u.pn * BM, slot, tid, wid); }
; #define PG8_BAR __builtin_amdgcn_s_barrier()
; template <class Epi, class Sched, bool ALIGN_EPI = false, bool SP2 = false>
; __device__ __forceinline__ void gemm_phase(PG8_LAS unsigned char* lds, const Gemm g, const Sched& S, const Epi& E) {
;     ...
;     for (int i = 0; i < 2; ++i) { int R, C; stage_rc(tid * 16 + i * 8192, R, C); const int Rb = Epi::PERM ? ((R & ~31) + perm32(R & 31)) : R;
;         voffA[i] = (unsigned)(R * K + C) * 2u; voffB[i] = (unsigned)(Rb * K + C) * 2u; }
;     const size_t kstep = (size_t)(BK * 2);
;     const size_t hstep = (size_t)HALF * K * 2;
;     const size_t tstep = 2 * hstep;
;     const unsigned ldsw = (unsigned)wid * 1024u;
;     const int aoff = lds_byte(wr * 64 + fr, fq * 8), boff = lds_byte(wc * 32 + fr, fq * 8);
;     ...
;     Unit cur, nxt; int ui = 0;
;     if (!S.next(0, cur)) return;
;     f32x4 acc[2][2][4][2];
; #pragma unroll
;     for (int a = 0; a < 2; ++a)
; #pragma unroll
;         for (int b = 0; b < 2; ++b)
; #pragma unroll
;             for (int m = 0; m < 4; ++m)
; #pragma unroll
;                 for (int n = 0; n < 2; ++n) acc[a][b][m][n] = (f32x4){0.f, 0.f, 0.f, 0.f};
;     bf16x8 At[4][2], B0[2][2], B1[2][2];
;     typename Epi::Pre pre;
;     const char* cA = (const char*)g.A + (size_t)cur.pm * tstep; const char* cB = (const char*)g.Bt + (size_t)cur.pn * tstep;
;     S.a_ready(cur);
;     E.prefetch(cur, lds + XSLOT_OFF, tid, wid);
;     if constexpr (SP2) {
;         PG8_STAGE(PG8_SB(0, 0), cB, voffB); PG8_STAGE(PG8_SB(0, 1), cB + hstep, voffB); PG8_STAGE(PG8_SA(0, 0), cA, voffA); PG8_STAGE(PG8_SA(0, 1), cA + hstep, voffA);
;         if (wr == 1) PG8_BAR;
.LBB0_504:
	v_lshrrev_b32_e32 v0, 26, v5
	v_add_u32_e32 v0, v4, v0
	v_ashrrev_i32_e32 v16, 6, v0
	v_bfe_i32 v0, v4, 27, 1
	v_lshlrev_b32_e32 v1, 4, v4
	v_lshrrev_b32_e32 v0, 22, v0
	v_add_u32_e32 v0, v1, v0
	v_and_b32_e32 v0, 0xfffffc00, v0
	v_sub_u32_e32 v0, v1, v0
	v_lshrrev_b32_e32 v3, 4, v0
	v_bitop3_b32 v3, v3, v0, 32 bitop3:0x6c
	v_ashrrev_i32_e32 v0, 31, v0
	v_lshrrev_b32_e32 v0, 26, v0
	s_ashr_i32 s29, s28, 31
	v_add_u32_e32 v0, v3, v0
	s_lshl_b64 s[2:3], s[28:29], 19
	v_readlane_b32 s16, v250, 4
	v_ashrrev_i32_e32 v17, 6, v0
	v_readlane_b32 s17, v250, 5
	s_add_u32 s2, s16, s2
	s_sext_i32_i16 s16, s55
	v_lshlrev_b32_e32 v8, 3, v16
	v_mul_i32_i24_e32 v9, 64, v17
	s_addc_u32 s3, s17, s3
	s_ashr_i32 s17, s16, 31
	v_and_b32_e32 v8, -16, v8
	v_sub_u32_e32 v3, v3, v9
	v_mov_b32_e32 v11, 1
	s_lshl_b64 s[16:17], s[16:17], 19
	v_add_u32_e32 v0, v17, v8
	v_ashrrev_i16_sdwa v3, v11, sext(v3) dst_sel:DWORD dst_unused:UNUSED_PAD src0_sel:DWORD src1_sel:BYTE_0
	s_add_u32 s30, s4, s16
	v_lshlrev_b32_e32 v8, 5, v16
	v_bfe_i32 v18, v3, 0, 16
	v_lshlrev_b32_e32 v3, 1, v0
	v_lshrrev_b32_e32 v9, 2, v0
	v_and_b32_e32 v10, 3, v17
	s_mov_b32 s16, 0x1fffe0
	v_and_b32_e32 v8, 32, v8
	v_and_b32_e32 v3, 24, v3
	v_and_b32_e32 v9, 4, v9
	v_and_or_b32 v10, v0, s16, v10
	v_or3_b32 v3, v10, v9, v3
	v_add_lshl_u32 v8, v8, v18, 1
	v_add_u32_e32 v1, 0x2000, v1
	v_lshl_add_u32 v164, v3, 11, v8
	v_ashrrev_i32_e32 v3, 31, v1
	v_lshrrev_b32_e32 v3, 22, v3
	v_add_u32_e32 v3, v1, v3
	v_ashrrev_i32_e32 v19, 10, v3
	v_mul_i32_i24_e32 v3, 0x400, v19
	v_sub_u32_e32 v1, v1, v3
	v_lshrrev_b32_e32 v3, 4, v1
	v_bitop3_b32 v1, v3, v1, 32 bitop3:0x6c
	v_lshl_add_u32 v0, v0, 11, v8
	v_ashrrev_i32_e32 v8, 31, v1
	v_lshrrev_b32_e32 v8, 26, v8
	v_add_u32_e32 v8, v1, v8
	v_lshlrev_b32_e32 v3, 3, v19
	v_ashrrev_i32_e32 v20, 6, v8
	v_and_b32_e32 v8, 0xc0, v8
	v_and_b32_e32 v3, -16, v3
	v_sub_u32_e32 v1, v1, v8
	v_add_u32_e32 v3, v20, v3
	v_ashrrev_i16_sdwa v1, v11, sext(v1) dst_sel:DWORD dst_unused:UNUSED_PAD src0_sel:DWORD src1_sel:BYTE_0
	s_addc_u32 s31, s5, s17
	v_lshlrev_b32_e32 v9, 5, v19
	v_bfe_i32 v21, v1, 0, 16
	v_lshlrev_b32_e32 v1, 1, v3
	v_lshrrev_b32_e32 v8, 2, v3
	v_and_b32_e32 v10, 3, v20
	s_add_i32 s29, s37, 0
	v_and_b32_e32 v9, 32, v9
	v_and_b32_e32 v1, 24, v1
	v_and_b32_e32 v8, 4, v8
	v_and_or_b32 v10, v3, s16, v10
	s_add_i32 m0, s29, 0x10000
	s_ashr_i32 s24, s18, 8
	v_or3_b32 v1, v10, v8, v1
	v_add_lshl_u32 v8, v9, v21, 1
	global_load_lds_dwordx4 v164, s[30:31]
	s_add_i32 m0, s29, 0x12000
	v_lshl_add_u32 v168, v1, 11, v8
	s_add_u32 s16, s30, 0x40000
	global_load_lds_dwordx4 v168, s[30:31]
	s_addc_u32 s17, s31, 0
	s_add_i32 m0, s29, 0x14000
	s_add_i32 s48, s29, 0x2000
	global_load_lds_dwordx4 v164, s[16:17]
	s_add_i32 m0, s29, 0x16000
	v_lshl_add_u32 v166, v3, 11, v8
	global_load_lds_dwordx4 v168, s[16:17]
	s_mov_b32 m0, s29
	s_add_u32 s16, s2, 0x40000
	global_load_lds_dwordx4 v0, s[2:3]
	s_mov_b32 m0, s48
	s_addc_u32 s17, s3, 0
	s_add_i32 s49, s29, 0x4000
	global_load_lds_dwordx4 v166, s[2:3]
	s_mov_b32 m0, s49
	s_add_i32 s50, s29, 0x6000
	global_load_lds_dwordx4 v0, s[16:17]
	s_mov_b32 m0, s50
	v_mov_b32_e32 v165, v2
	global_load_lds_dwordx4 v166, s[16:17]
	v_mov_b32_e32 v169, v2
	v_mov_b32_e32 v1, v2
	v_mov_b32_e32 v167, v2
	s_cmp_eq_u32 s24, 1
	v_mov_b32_e32 v218, 0x358637bd
	s_waitcnt lgkmcnt(0)
	v_lshl_add_u64 v[14:15], s[30:31], 0, v[164:165]
	v_lshl_add_u64 v[12:13], s[30:31], 0, v[168:169]
	v_lshl_add_u64 v[8:9], s[2:3], 0, v[0:1]
	s_cselect_b64 s[16:17], -1, 0
	s_cmp_lg_u32 s24, 1
	v_lshl_add_u64 v[10:11], s[2:3], 0, v[166:167]
	s_setprio 1
	s_cbranch_scc1 .LBB0_506
	s_setprio 0
	s_barrier
